# v112 + waitcnt placement in grid barrier: barrier-pointer s_load issued before the L2 writeback wait so it overlaps
# speedup vs baseline: 1.0006x; 1.0006x over previous
; __global__ void __launch_bounds__(256, 2) mega_kernel(Params p) {
;     ...
;     if (ph + 1 < NPHASE) {
;       if (ph == 0) grid.sync();
;       else xcd_barrier(bar, xcc, nloc, nx);
.LBB0_2906:
	s_and_b64 vcc, exec, s[0:1]
	s_cbranch_vccz .LBB0_2961
	s_waitcnt lgkmcnt(0)
	s_barrier
	s_mov_b64 s[0:1], exec
	v_readlane_b32 s4, v246, 49
	v_readlane_b32 s5, v246, 50
	s_and_b64 s[4:5], s[0:1], s[4:5]
	s_mov_b64 exec, s[4:5]
	s_cbranch_execz .LBB0_2917
	s_load_dwordx2 s[4:5], s[58:59], 0x58
	buffer_wbl2 sc1
	s_waitcnt vmcnt(0)
	s_mov_b64 s[6:7], exec
	v_mbcnt_lo_u32_b32 v10, s6, 0
	v_mbcnt_hi_u32_b32 v10, s7, v10
	v_cmp_eq_u32_e32 vcc, 0, v10
	s_waitcnt lgkmcnt(0)
	global_load_dword v8, v9, s[4:5] offset:40
	s_and_saveexec_b64 s[8:9], vcc
	s_cbranch_execz .LBB0_2910
	s_bcnt1_i32_b64 s2, s[6:7]
	v_mov_b32_e32 v11, s2
	global_atomic_add v11, v9, v11, s[4:5] offset:32 sc0
